# P5 phase-start stagger: blocks 64..239 start 0-16us late (ramp) to spread the residual epilogue HBM burst
# speedup vs baseline: 1.0046x; 1.0046x over previous
.LBB0_1315:
	s_or_b64 exec, exec, s[0:1]
	s_add_u32 s0, s50, 0x495a014
	s_addc_u32 s1, s51, 0
	s_add_i32 s2, s92, -16
	v_readlane_b32 s6, v254, 50
	s_cmp_ge_i32 s6, s2
	s_waitcnt lgkmcnt(0)
	s_barrier
	s_cselect_b32 s101, 1, 0
	v_readlane_b32 s100, v254, 50
	s_nop 0
	s_sub_i32 s100, s100, 64
	s_cmp_lt_u32 s100, 176
	s_cbranch_scc0 .Lstg_done_B6
	s_mul_i32 s100, s100, 9
	s_memrealtime s[98:99]
	s_waitcnt lgkmcnt(0)
	s_add_u32 s100, s98, s100
.Lstg_spin_B6:
	s_sleep 2
	s_memrealtime s[98:99]
	s_waitcnt lgkmcnt(0)
	s_sub_u32 s99, s100, s98
	s_cmp_gt_i32 s99, 0
	s_cbranch_scc1 .Lstg_spin_B6
.Lstg_done_B6:
	s_cmp_lg_u32 s101, 0
	v_readlane_b32 s7, v254, 51
	s_cbranch_scc0 .LBB0_1324
	v_mov_b32_e32 v16, v250
	s_sub_i32 s2, s6, s2
	v_bfe_i32 v2, v16, 27, 1
	v_lshlrev_b32_e32 v1, 4, v16
	v_lshrrev_b32_e32 v2, 22, v2
	v_add_u32_e32 v2, v1, v2
	v_and_b32_e32 v2, 0xfffffc00, v2
	v_ashrrev_i32_e32 v0, 31, v16
	v_sub_u32_e32 v2, v1, v2
	s_lshr_b32 s8, s2, 1
	s_and_b32 s2, s2, 1
	v_lshrrev_b32_e32 v0, 26, v0
	v_lshrrev_b32_e32 v3, 4, v2
	s_lshl_b32 s6, s2, 21
	v_add_u32_e32 v0, v16, v0
	v_bitop3_b32 v3, v3, v2, 32 bitop3:0x6c
	v_ashrrev_i32_e32 v2, 31, v2
	s_add_u32 s4, s4, s6
	v_ashrrev_i32_e32 v0, 6, v0
	v_lshrrev_b32_e32 v2, 26, v2
	s_addc_u32 s5, s5, 0
	s_lshl_b32 s6, s8, 10
	v_lshlrev_b32_e32 v4, 3, v0
	v_add_u32_e32 v2, v3, v2
	s_add_u32 s6, s4, s6
	v_and_b32_e32 v4, -16, v4
	v_ashrrev_i32_e32 v2, 6, v2
	s_addc_u32 s7, s5, 0
	s_lshl_b32 s4, s8, 7
	v_add_u32_e32 v4, v2, v4
	v_mul_i32_i24_e32 v2, 64, v2
	s_mov_b32 s9, 0
	s_add_i32 s8, s4, 0x400
	v_sub_u32_e32 v2, v3, v2
	v_mov_b32_e32 v5, 1
	s_lshl_b64 s[8:9], s[8:9], 10
	v_readlane_b32 s10, v254, 34
	v_lshlrev_b32_e32 v0, 5, v0
	v_ashrrev_i16_sdwa v2, v5, sext(v2) dst_sel:DWORD dst_unused:UNUSED_PAD src0_sel:DWORD src1_sel:BYTE_0
	v_readlane_b32 s11, v254, 35
	s_add_u32 s8, s10, s8
	v_and_b32_e32 v0, 32, v0
	v_bfe_i32 v2, v2, 0, 16
	v_lshlrev_b32_e32 v3, 12, v4
	s_addc_u32 s9, s11, s9
	v_add3_u32 v0, v0, v2, v3
	s_movk_i32 s11, 0xf200
	v_mad_u64_u32 v[2:3], s[12:13], v4, s11, v[0:1]
	v_add_u32_e32 v1, 0x2000, v1
	v_ashrrev_i32_e32 v3, 31, v1
	v_lshrrev_b32_e32 v3, 22, v3
	v_add_u32_e32 v3, v1, v3
	v_ashrrev_i32_e32 v3, 10, v3
	v_mul_i32_i24_e32 v4, 0x400, v3
	v_sub_u32_e32 v1, v1, v4
	v_lshrrev_b32_e32 v4, 4, v1
	v_bitop3_b32 v1, v4, v1, 32 bitop3:0x6c
	v_ashrrev_i32_e32 v6, 31, v1
	v_lshrrev_b32_e32 v6, 26, v6
	v_add_u32_e32 v6, v1, v6
	v_lshlrev_b32_e32 v4, 3, v3
	v_ashrrev_i32_e32 v7, 6, v6
	v_and_b32_e32 v6, 0xc0, v6
	v_and_b32_e32 v4, -16, v4
	v_sub_u32_e32 v1, v1, v6
	v_add_u32_e32 v4, v7, v4
	v_lshlrev_b32_e32 v3, 5, v3
	v_ashrrev_i16_sdwa v1, v5, sext(v1) dst_sel:DWORD dst_unused:UNUSED_PAD src0_sel:DWORD src1_sel:BYTE_0
	v_and_b32_e32 v3, 32, v3
	v_bfe_i32 v1, v1, 0, 16
	v_lshlrev_b32_e32 v5, 12, v4
	v_add3_u32 v10, v3, v1, v5
	v_readfirstlane_b32 s5, v16
	v_mad_u64_u32 v[6:7], s[12:13], v4, s11, v[10:11]
	s_ashr_i32 s12, s5, 6
	s_lshl_b32 s28, s12, 10
	v_ashrrev_i32_e32 v3, 31, v2
	s_add_i32 s26, s28, 32
	v_lshlrev_b64 v[4:5], 1, v[2:3]
	v_ashrrev_i32_e32 v7, 31, v6
	s_add_i32 m0, s26, 0x10000
	v_lshl_add_u64 v[12:13], s[8:9], 0, v[4:5]
	v_lshlrev_b64 v[6:7], 1, v[6:7]
	v_ashrrev_i32_e32 v1, 31, v0
	s_ashr_i32 s10, s5, 8
	global_load_lds_dwordx4 v[12:13], off
	v_lshl_add_u64 v[14:15], s[8:9], 0, v[6:7]
	s_add_i32 m0, s26, 0x12000
	v_lshlrev_b64 v[0:1], 1, v[0:1]
	v_ashrrev_i32_e32 v11, 31, v10
	s_add_i32 s27, s26, 0x2000
	global_load_lds_dwordx4 v[14:15], off
	v_lshl_add_u64 v[8:9], s[6:7], 0, v[0:1]
	s_mov_b32 m0, s26
	v_lshlrev_b64 v[2:3], 1, v[10:11]
	s_add_u32 s14, s8, 0x20000
	global_load_lds_dwordx4 v[8:9], off
	v_lshl_add_u64 v[10:11], s[6:7], 0, v[2:3]
	s_mov_b32 m0, s27
	s_addc_u32 s15, s9, 0
	s_add_i32 s25, s26, 0x14000
	global_load_lds_dwordx4 v[10:11], off
	v_lshl_add_u64 v[18:19], s[14:15], 0, v[4:5]
	s_mov_b32 m0, s25
	s_add_i32 s23, s26, 0x16000
	global_load_lds_dwordx4 v[18:19], off
	v_lshl_add_u64 v[18:19], s[14:15], 0, v[6:7]
	s_add_u32 s14, s6, 0x100000
	s_mov_b32 m0, s23
	s_addc_u32 s15, s7, 0
	s_add_i32 s22, s26, 0x4000
	global_load_lds_dwordx4 v[18:19], off
	v_lshl_add_u64 v[18:19], s[14:15], 0, v[0:1]
	s_mov_b32 m0, s22
	s_add_i32 s19, s26, 0x6000
	global_load_lds_dwordx4 v[18:19], off
	v_lshl_add_u64 v[18:19], s[14:15], 0, v[2:3]
	s_mov_b32 m0, s19
	s_cmp_lg_u32 s10, 1
	global_load_lds_dwordx4 v[18:19], off
	s_cbranch_scc1 .LBB0_1318
	s_barrier
